# stack + merged vmcnt waits before the GEMM staging writes (one wait per operand instead of a ladder)
# baseline (speedup 1.0000x reference)
; #pragma unroll
;   for (int ks = KS0; ks < KS1; ++ks) {
;     bf16x8 af[8], bfr[4];
; #pragma unroll
;     for (int i = 0; i < 8; ++i) {
;       const int r = wm * 128 + i * 16 + (lane & 15);
;       af[i] = *(const bf16x8*)(S + r * 64 + (((ks * 4 + (lane >> 4)) ^ ((r >> 1) & 7)) << 3));
;     }
; #pragma unroll
;     for (int j = 0; j < 4; ++j) {
;       const int r = wn * 64 + j * 16 + (lane & 15);
;       bfr[j] = *(const bf16x8*)(S + 16384 + r * 64 + (((ks * 4 + (lane >> 4)) ^ ((r >> 1) & 7)) << 3));
;     }
;     __builtin_amdgcn_s_setprio(1);
; #pragma unroll
;     for (int i = 0; i < 8; ++i)
; #pragma unroll
;       for (int j = 0; j < 4; ++j) acc[i][j] = mfma16(bfr[j], af[i], acc[i][j]);
;     __builtin_amdgcn_s_setprio(0);
;   }
; }
; DI void g8_load1o(u32x4 (&r4)[4], const bf16_t* base, const unsigned (&off)[4]) {
; #pragma unroll
;   for (int i = 0; i < 4; ++i) r4[i] = *(const u32x4*)(base + off[i]);
; }
; DI void gemm8_accum(f32x4 (&acc)[8][4], const bf16_t* a, size_t lda, const bf16_t* b, size_t ldb, int nkb, bf16_t* L,
;                     const bool pre, const bf16_t* an, size_t ldan, const bf16_t* bn, size_t ldbn) {
;   const int tid = TID8(), lane = tid & 63, w = tid >> 6;
;   const int wm = w >> 2, wn = w & 3;
;   const int lrow = tid >> 3, lch = tid & 7;
;   u32x4 ra[4], rb[4];
;   unsigned offa[4], offb[4];
; #pragma unroll
;   for (int i = 0; i < 4; ++i) {
;     offa[i] = (unsigned)(lrow + 64 * i) * (unsigned)lda + (unsigned)(lch * 8);
;     offb[i] = (unsigned)(lrow + 64 * i) * (unsigned)ldb + (unsigned)(lch * 8);
;   }
;   if (!pre) {
;     g8_load1o(ra, a, offa);
;     g8_load1o(rb, b, offb);
;     __syncthreads();
;     g8_store(L, ra, rb, lrow, lch);
;   }
;   g8_load1o(ra, a + 64, offa);
;   g8_load1o(rb, b + 64, offb);
;   for (int kb = 0; kb + 2 < nkb; ++kb) {
;     __syncthreads();
;     g8_store1(L + ((kb + 1) & 1) * 32768, ra, lrow, lch);
;     g8_load1o(ra, a + (kb + 2) * 64, offa);
;     __builtin_amdgcn_sched_barrier(0);
;     g8_compute<0, 1>(acc, L + (kb & 1) * 32768, wm, wn, lane);
;     __builtin_amdgcn_sched_barrier(0);
;     g8_store1(L + ((kb + 1) & 1) * 32768 + 16384, rb, lrow, lch);
;     g8_load1o(rb, b + (kb + 2) * 64, offb);
;     __builtin_amdgcn_sched_barrier(0);
;     g8_compute<1, 2>(acc, L + (kb & 1) * 32768, wm, wn, lane);
;   }
.Lstg_134_a:
	s_waitcnt vmcnt(4)
	ds_write_b128 v167, v[22:25]
	ds_write_b128 v167, v[18:21] offset:8192
	ds_write_b128 v167, v[26:29] offset:16384
	ds_write_b128 v167, v[30:33] offset:24576
	s_add_u32 s54, s52, s0
	s_addc_u32 s55, s53, s1
	global_load_dwordx4 v[22:25], v185, s[54:55]
	global_load_dwordx4 v[26:29], v181, s[54:55]
	global_load_dwordx4 v[18:21], v183, s[54:55]
	global_load_dwordx4 v[30:33], v179, s[54:55]
	s_and_b32 s2, s2, 0x8000
	s_lshl_b32 s2, s2, 1
	v_lshl_add_u32 v169, v191, 1, s2
	v_add_u32_e32 v198, v169, v187
	ds_read_b128 v[192:195], v198
	ds_read_b128 v[206:209], v198 offset:2048
	ds_read_b128 v[210:213], v198 offset:4096
	ds_read_b128 v[214:217], v198 offset:6144
	ds_read_b128 v[218:221], v198 offset:8192
	ds_read_b128 v[222:225], v198 offset:10240
	ds_read_b128 v[226:229], v198 offset:12288
	ds_read_b128 v[230:233], v198 offset:14336
	v_add_u32_e32 v169, v169, v186
	ds_read_b128 v[234:237], v169 offset:32768
	ds_read_b128 v[238:241], v169 offset:34816
	ds_read_b128 v[242:245], v169 offset:36864
	ds_read_b128 v[246:249], v169 offset:38912
	s_waitcnt lgkmcnt(3)
	v_mfma_f32_16x16x32_bf16 v[34:37], v[234:237], v[192:195], v[34:37]
	s_waitcnt lgkmcnt(2)
	v_mfma_f32_16x16x32_bf16 v[38:41], v[238:241], v[192:195], v[38:41]
	s_waitcnt lgkmcnt(1)
	v_mfma_f32_16x16x32_bf16 v[42:45], v[242:245], v[192:195], v[42:45]
	s_waitcnt lgkmcnt(0)
	v_mfma_f32_16x16x32_bf16 v[46:49], v[246:249], v[192:195], v[46:49]
	v_mfma_f32_16x16x32_bf16 v[50:53], v[234:237], v[206:209], v[50:53]
	v_mfma_f32_16x16x32_bf16 v[54:57], v[238:241], v[206:209], v[54:57]
	v_mfma_f32_16x16x32_bf16 v[58:61], v[242:245], v[206:209], v[58:61]
	v_mfma_f32_16x16x32_bf16 v[62:65], v[246:249], v[206:209], v[62:65]
	v_mfma_f32_16x16x32_bf16 v[66:69], v[234:237], v[210:213], v[66:69]
	v_mfma_f32_16x16x32_bf16 v[70:73], v[238:241], v[210:213], v[70:73]
	v_mfma_f32_16x16x32_bf16 v[74:77], v[242:245], v[210:213], v[74:77]
	v_mfma_f32_16x16x32_bf16 v[78:81], v[246:249], v[210:213], v[78:81]
	v_mfma_f32_16x16x32_bf16 v[82:85], v[234:237], v[214:217], v[82:85]
	v_mfma_f32_16x16x32_bf16 v[86:89], v[238:241], v[214:217], v[86:89]
	v_mfma_f32_16x16x32_bf16 v[90:93], v[242:245], v[214:217], v[90:93]
	v_mfma_f32_16x16x32_bf16 v[94:97], v[246:249], v[214:217], v[94:97]
	v_mfma_f32_16x16x32_bf16 v[98:101], v[234:237], v[218:221], v[98:101]
	v_mfma_f32_16x16x32_bf16 v[102:105], v[238:241], v[218:221], v[102:105]
	v_mfma_f32_16x16x32_bf16 v[106:109], v[242:245], v[218:221], v[106:109]
	v_mfma_f32_16x16x32_bf16 v[110:113], v[246:249], v[218:221], v[110:113]
	v_mfma_f32_16x16x32_bf16 v[114:117], v[234:237], v[222:225], v[114:117]
	v_mfma_f32_16x16x32_bf16 v[118:121], v[238:241], v[222:225], v[118:121]
	v_mfma_f32_16x16x32_bf16 v[122:125], v[242:245], v[222:225], v[122:125]
	v_mfma_f32_16x16x32_bf16 v[126:129], v[246:249], v[222:225], v[126:129]
	v_mfma_f32_16x16x32_bf16 v[130:133], v[234:237], v[226:229], v[130:133]
	v_mfma_f32_16x16x32_bf16 v[134:137], v[238:241], v[226:229], v[134:137]
	v_mfma_f32_16x16x32_bf16 v[138:141], v[242:245], v[226:229], v[138:141]
	v_mfma_f32_16x16x32_bf16 v[142:145], v[246:249], v[226:229], v[142:145]
	v_mfma_f32_16x16x32_bf16 v[146:149], v[234:237], v[230:233], v[146:149]
	v_mfma_f32_16x16x32_bf16 v[150:153], v[238:241], v[230:233], v[150:153]
	v_mfma_f32_16x16x32_bf16 v[154:157], v[242:245], v[230:233], v[154:157]
	v_mfma_f32_16x16x32_bf16 v[158:161], v[246:249], v[230:233], v[158:161]
	s_waitcnt vmcnt(4)
	ds_write_b128 v167, v[6:9] offset:32768
	ds_write_b128 v167, v[2:5] offset:40960
	ds_write_b128 v167, v[10:13] offset:49152
	ds_write_b128 v167, v[14:17] offset:57344
	s_add_u32 s58, s56, s0
	s_addc_u32 s59, s57, s1
	global_load_dwordx4 v[6:9], v177, s[58:59]
	global_load_dwordx4 v[2:5], v175, s[58:59]
	global_load_dwordx4 v[10:13], v173, s[58:59]
	global_load_dwordx4 v[14:17], v171, s[58:59]
	v_lshl_add_u32 v167, v188, 1, s2
	v_add_u32_e32 v169, v167, v187
	ds_read_b128 v[192:195], v169
	ds_read_b128 v[206:209], v169 offset:2048
	ds_read_b128 v[210:213], v169 offset:4096
	ds_read_b128 v[214:217], v169 offset:6144
	ds_read_b128 v[218:221], v169 offset:8192
	ds_read_b128 v[222:225], v169 offset:10240
	ds_read_b128 v[226:229], v169 offset:12288
	ds_read_b128 v[230:233], v169 offset:14336
	v_add_u32_e32 v167, v167, v186
	ds_read_b128 v[234:237], v167 offset:32768
	ds_read_b128 v[238:241], v167 offset:34816
	ds_read_b128 v[242:245], v167 offset:36864
	ds_read_b128 v[246:249], v167 offset:38912
	s_cmp_lg_u32 s101, 0
	s_cbranch_scc1 .Lstg_134_b
	s_waitcnt lgkmcnt(3)
	v_mfma_f32_16x16x32_bf16 v[34:37], v[234:237], v[192:195], v[34:37]
	s_waitcnt lgkmcnt(2)
	v_mfma_f32_16x16x32_bf16 v[38:41], v[238:241], v[192:195], v[38:41]
	s_waitcnt lgkmcnt(1)
	v_mfma_f32_16x16x32_bf16 v[42:45], v[242:245], v[192:195], v[42:45]
	s_waitcnt lgkmcnt(0)
	v_mfma_f32_16x16x32_bf16 v[46:49], v[246:249], v[192:195], v[46:49]
	v_mfma_f32_16x16x32_bf16 v[50:53], v[234:237], v[206:209], v[50:53]
	v_mfma_f32_16x16x32_bf16 v[54:57], v[238:241], v[206:209], v[54:57]
	v_mfma_f32_16x16x32_bf16 v[58:61], v[242:245], v[206:209], v[58:61]
	v_mfma_f32_16x16x32_bf16 v[62:65], v[246:249], v[206:209], v[62:65]
	v_mfma_f32_16x16x32_bf16 v[66:69], v[234:237], v[210:213], v[66:69]
	v_mfma_f32_16x16x32_bf16 v[70:73], v[238:241], v[210:213], v[70:73]
	v_mfma_f32_16x16x32_bf16 v[74:77], v[242:245], v[210:213], v[74:77]
	v_mfma_f32_16x16x32_bf16 v[78:81], v[246:249], v[210:213], v[78:81]
	v_mfma_f32_16x16x32_bf16 v[82:85], v[234:237], v[214:217], v[82:85]
	v_mfma_f32_16x16x32_bf16 v[86:89], v[238:241], v[214:217], v[86:89]
	v_mfma_f32_16x16x32_bf16 v[90:93], v[242:245], v[214:217], v[90:93]
	v_mfma_f32_16x16x32_bf16 v[94:97], v[246:249], v[214:217], v[94:97]
	v_mfma_f32_16x16x32_bf16 v[98:101], v[234:237], v[218:221], v[98:101]
	v_mfma_f32_16x16x32_bf16 v[102:105], v[238:241], v[218:221], v[102:105]
	v_mfma_f32_16x16x32_bf16 v[106:109], v[242:245], v[218:221], v[106:109]
	v_mfma_f32_16x16x32_bf16 v[110:113], v[246:249], v[218:221], v[110:113]
	v_mfma_f32_16x16x32_bf16 v[114:117], v[234:237], v[222:225], v[114:117]
	v_mfma_f32_16x16x32_bf16 v[118:121], v[238:241], v[222:225], v[118:121]
	v_mfma_f32_16x16x32_bf16 v[122:125], v[242:245], v[222:225], v[122:125]
	v_mfma_f32_16x16x32_bf16 v[126:129], v[246:249], v[222:225], v[126:129]
	v_mfma_f32_16x16x32_bf16 v[130:133], v[234:237], v[226:229], v[130:133]
	v_mfma_f32_16x16x32_bf16 v[134:137], v[238:241], v[226:229], v[134:137]
	v_mfma_f32_16x16x32_bf16 v[138:141], v[242:245], v[226:229], v[138:141]
	v_mfma_f32_16x16x32_bf16 v[142:145], v[246:249], v[226:229], v[142:145]
	v_mfma_f32_16x16x32_bf16 v[146:149], v[234:237], v[230:233], v[146:149]
	v_mfma_f32_16x16x32_bf16 v[150:153], v[238:241], v[230:233], v[150:153]
	v_mfma_f32_16x16x32_bf16 v[154:157], v[242:245], v[230:233], v[154:157]
	v_mfma_f32_16x16x32_bf16 v[158:161], v[246:249], v[230:233], v[158:161]

; template <bool FX>
; DI void nsa_tile(const Params& p, int b, int g, int tile, bf16_t* lds, const float CL) {
;     ...
;       for (int s = 0; s <= cur; ++s) {
;         __syncthreads();
;         tile64_sstore(tid, Ks, rk0, rk1);
;         tile64_sstore(tid, Vs, rv0, rv1);
;         __syncthreads();
;         if (s < cur) {
;           tile64_gload(tid, rk0, rk1, kb + (size_t)(s + 1) * 64 * ZS, ZS);
;           tile64_gload(tid, rv0, rv1, vsT + (s + 1) * 64, TS);
;         }
;         uint32_t wsel = (s < 32) ? sw0 : (s < 64) ? sw1 : (s < 96) ? sw2 : sw3;
;         bool sel = (wsel >> (s & 31)) & 1u;
;         int hi = sel ? (tok - s * 64) : -1;
;         if (__any(hi >= 0)) attn_compute<2, FX>(lane, Ks, Vs, qf, st, invl, 0, hi, dA, dE, CL);
.LBB0_667_p1:
	s_cmp_eq_u32 s25, s68
	v_subrev_u32_e32 v187, 64, v187
	s_cbranch_scc1 .LBB0_675

; #pragma unroll
;   for (int ks = KS0; ks < KS1; ++ks) {
;     bf16x8 af[8], bfr[4];
; #pragma unroll
;     for (int i = 0; i < 8; ++i) {
;       const int r = wm * 128 + i * 16 + (lane & 15);
;       af[i] = *(const bf16x8*)(S + r * 64 + (((ks * 4 + (lane >> 4)) ^ ((r >> 1) & 7)) << 3));
;     }
; #pragma unroll
;     for (int j = 0; j < 4; ++j) {
;       const int r = wn * 64 + j * 16 + (lane & 15);
;       bfr[j] = *(const bf16x8*)(S + 16384 + r * 64 + (((ks * 4 + (lane >> 4)) ^ ((r >> 1) & 7)) << 3));
;     }
;     __builtin_amdgcn_s_setprio(1);
; #pragma unroll
;     for (int i = 0; i < 8; ++i)
; #pragma unroll
;       for (int j = 0; j < 4; ++j) acc[i][j] = mfma16(bfr[j], af[i], acc[i][j]);
;     __builtin_amdgcn_s_setprio(0);
;   }
; }
; DI void g8_load1o(u32x4 (&r4)[4], const bf16_t* base, const unsigned (&off)[4]) {
; #pragma unroll
;   for (int i = 0; i < 4; ++i) r4[i] = *(const u32x4*)(base + off[i]);
; }
; DI void gemm8_accum(f32x4 (&acc)[8][4], const bf16_t* a, size_t lda, const bf16_t* b, size_t ldb, int nkb, bf16_t* L,
;                     const bool pre, const bf16_t* an, size_t ldan, const bf16_t* bn, size_t ldbn) {
;   const int tid = TID8(), lane = tid & 63, w = tid >> 6;
;   const int wm = w >> 2, wn = w & 3;
;   const int lrow = tid >> 3, lch = tid & 7;
;   u32x4 ra[4], rb[4];
;   unsigned offa[4], offb[4];
; #pragma unroll
;   for (int i = 0; i < 4; ++i) {
;     offa[i] = (unsigned)(lrow + 64 * i) * (unsigned)lda + (unsigned)(lch * 8);
;     offb[i] = (unsigned)(lrow + 64 * i) * (unsigned)ldb + (unsigned)(lch * 8);
;   }
;   if (!pre) {
;     g8_load1o(ra, a, offa);
;     g8_load1o(rb, b, offb);
;     __syncthreads();
;     g8_store(L, ra, rb, lrow, lch);
;   }
;   g8_load1o(ra, a + 64, offa);
;   g8_load1o(rb, b + 64, offb);
;   for (int kb = 0; kb + 2 < nkb; ++kb) {
;     __syncthreads();
;     g8_store1(L + ((kb + 1) & 1) * 32768, ra, lrow, lch);
;     g8_load1o(ra, a + (kb + 2) * 64, offa);
;     __builtin_amdgcn_sched_barrier(0);
;     g8_compute<0, 1>(acc, L + (kb & 1) * 32768, wm, wn, lane);
;     __builtin_amdgcn_sched_barrier(0);
;     g8_store1(L + ((kb + 1) & 1) * 32768 + 16384, rb, lrow, lch);
;     g8_load1o(rb, b + (kb + 2) * 64, offb);
;     __builtin_amdgcn_sched_barrier(0);
;     g8_compute<1, 2>(acc, L + (kb & 1) * 32768, wm, wn, lane);
;   }
.Lstg_778_a:
	s_waitcnt vmcnt(4)
	ds_write_b128 v191, v[22:25]
	ds_write_b128 v191, v[18:21] offset:8192
	ds_write_b128 v191, v[26:29] offset:16384
	ds_write_b128 v191, v[30:33] offset:24576
	s_add_u32 s54, s52, s0
	s_addc_u32 s55, s53, s1
	global_load_dwordx4 v[22:25], v187, s[54:55]
	global_load_dwordx4 v[26:29], v183, s[54:55]
	global_load_dwordx4 v[18:21], v185, s[54:55]
	global_load_dwordx4 v[30:33], v181, s[54:55]
	s_and_b32 s2, s2, 0x8000
	s_lshl_b32 s2, s2, 1
	v_lshl_add_u32 v202, v169, 1, s2
	v_add_u32_e32 v203, v202, v188
	ds_read_b128 v[192:195], v203
	ds_read_b128 v[198:201], v203 offset:2048
	ds_read_b128 v[206:209], v203 offset:4096
	ds_read_b128 v[210:213], v203 offset:6144
	ds_read_b128 v[214:217], v203 offset:8192
	ds_read_b128 v[218:221], v203 offset:10240
	ds_read_b128 v[222:225], v203 offset:12288
	ds_read_b128 v[226:229], v203 offset:14336
	v_add_u32_e32 v202, v202, v171
	ds_read_b128 v[230:233], v202 offset:32768
	ds_read_b128 v[234:237], v202 offset:34816
	ds_read_b128 v[238:241], v202 offset:36864
	ds_read_b128 v[242:245], v202 offset:38912
	s_waitcnt lgkmcnt(3)
	v_mfma_f32_16x16x32_bf16 v[158:161], v[230:233], v[192:195], v[158:161]
	s_waitcnt lgkmcnt(2)
	v_mfma_f32_16x16x32_bf16 v[154:157], v[234:237], v[192:195], v[154:157]
	s_waitcnt lgkmcnt(1)
	v_mfma_f32_16x16x32_bf16 v[150:153], v[238:241], v[192:195], v[150:153]
	s_waitcnt lgkmcnt(0)
	v_mfma_f32_16x16x32_bf16 v[146:149], v[242:245], v[192:195], v[146:149]
	v_mfma_f32_16x16x32_bf16 v[142:145], v[230:233], v[198:201], v[142:145]
	v_mfma_f32_16x16x32_bf16 v[138:141], v[234:237], v[198:201], v[138:141]
	v_mfma_f32_16x16x32_bf16 v[134:137], v[238:241], v[198:201], v[134:137]
	v_mfma_f32_16x16x32_bf16 v[130:133], v[242:245], v[198:201], v[130:133]
	v_mfma_f32_16x16x32_bf16 v[126:129], v[230:233], v[206:209], v[126:129]
	v_mfma_f32_16x16x32_bf16 v[122:125], v[234:237], v[206:209], v[122:125]
	v_mfma_f32_16x16x32_bf16 v[118:121], v[238:241], v[206:209], v[118:121]
	v_mfma_f32_16x16x32_bf16 v[114:117], v[242:245], v[206:209], v[114:117]
	v_mfma_f32_16x16x32_bf16 v[110:113], v[230:233], v[210:213], v[110:113]
	v_mfma_f32_16x16x32_bf16 v[106:109], v[234:237], v[210:213], v[106:109]
	v_mfma_f32_16x16x32_bf16 v[102:105], v[238:241], v[210:213], v[102:105]
	v_mfma_f32_16x16x32_bf16 v[98:101], v[242:245], v[210:213], v[98:101]
	v_mfma_f32_16x16x32_bf16 v[94:97], v[230:233], v[214:217], v[94:97]
	v_mfma_f32_16x16x32_bf16 v[90:93], v[234:237], v[214:217], v[90:93]
	v_mfma_f32_16x16x32_bf16 v[86:89], v[238:241], v[214:217], v[86:89]
	v_mfma_f32_16x16x32_bf16 v[82:85], v[242:245], v[214:217], v[82:85]
	v_mfma_f32_16x16x32_bf16 v[78:81], v[230:233], v[218:221], v[78:81]
	v_mfma_f32_16x16x32_bf16 v[74:77], v[234:237], v[218:221], v[74:77]
	v_mfma_f32_16x16x32_bf16 v[70:73], v[238:241], v[218:221], v[70:73]
	v_mfma_f32_16x16x32_bf16 v[66:69], v[242:245], v[218:221], v[66:69]
	v_mfma_f32_16x16x32_bf16 v[62:65], v[230:233], v[222:225], v[62:65]
	v_mfma_f32_16x16x32_bf16 v[58:61], v[234:237], v[222:225], v[58:61]
	v_mfma_f32_16x16x32_bf16 v[54:57], v[238:241], v[222:225], v[54:57]
	v_mfma_f32_16x16x32_bf16 v[50:53], v[242:245], v[222:225], v[50:53]
	v_mfma_f32_16x16x32_bf16 v[46:49], v[230:233], v[226:229], v[46:49]
	v_mfma_f32_16x16x32_bf16 v[42:45], v[234:237], v[226:229], v[42:45]
	v_mfma_f32_16x16x32_bf16 v[38:41], v[238:241], v[226:229], v[38:41]
	v_mfma_f32_16x16x32_bf16 v[34:37], v[242:245], v[226:229], v[34:37]
	s_waitcnt vmcnt(4)
	ds_write_b128 v191, v[14:17] offset:32768
	ds_write_b128 v191, v[2:5] offset:40960
	ds_write_b128 v191, v[6:9] offset:49152
	ds_write_b128 v191, v[10:13] offset:57344
	s_add_u32 s58, s56, s0
	s_addc_u32 s59, s57, s1
	global_load_dwordx4 v[14:17], v179, s[58:59]
	global_load_dwordx4 v[2:5], v177, s[58:59]
	global_load_dwordx4 v[6:9], v175, s[58:59]
	global_load_dwordx4 v[10:13], v173, s[58:59]
	v_lshl_add_u32 v191, v189, 1, s2
	v_add_u32_e32 v202, v191, v188
	ds_read_b128 v[192:195], v202
	ds_read_b128 v[198:201], v202 offset:2048
	ds_read_b128 v[206:209], v202 offset:4096
	ds_read_b128 v[210:213], v202 offset:6144
	ds_read_b128 v[214:217], v202 offset:8192
	ds_read_b128 v[218:221], v202 offset:10240
	ds_read_b128 v[222:225], v202 offset:12288
	ds_read_b128 v[226:229], v202 offset:14336
	v_add_u32_e32 v191, v191, v171
	ds_read_b128 v[230:233], v191 offset:32768
	ds_read_b128 v[234:237], v191 offset:34816
	ds_read_b128 v[238:241], v191 offset:36864
	ds_read_b128 v[242:245], v191 offset:38912
	s_cmp_lg_u32 s101, 0
	s_cbranch_scc1 .Lstg_778_b
	s_waitcnt lgkmcnt(3)
	v_mfma_f32_16x16x32_bf16 v[158:161], v[230:233], v[192:195], v[158:161]
	s_waitcnt lgkmcnt(2)
	v_mfma_f32_16x16x32_bf16 v[154:157], v[234:237], v[192:195], v[154:157]
	s_waitcnt lgkmcnt(1)
	v_mfma_f32_16x16x32_bf16 v[150:153], v[238:241], v[192:195], v[150:153]
	s_waitcnt lgkmcnt(0)
	v_mfma_f32_16x16x32_bf16 v[146:149], v[242:245], v[192:195], v[146:149]
	v_mfma_f32_16x16x32_bf16 v[142:145], v[230:233], v[198:201], v[142:145]
	v_mfma_f32_16x16x32_bf16 v[138:141], v[234:237], v[198:201], v[138:141]
	v_mfma_f32_16x16x32_bf16 v[134:137], v[238:241], v[198:201], v[134:137]
	v_mfma_f32_16x16x32_bf16 v[130:133], v[242:245], v[198:201], v[130:133]
	v_mfma_f32_16x16x32_bf16 v[126:129], v[230:233], v[206:209], v[126:129]
	v_mfma_f32_16x16x32_bf16 v[122:125], v[234:237], v[206:209], v[122:125]
	v_mfma_f32_16x16x32_bf16 v[118:121], v[238:241], v[206:209], v[118:121]
	v_mfma_f32_16x16x32_bf16 v[114:117], v[242:245], v[206:209], v[114:117]
	v_mfma_f32_16x16x32_bf16 v[110:113], v[230:233], v[210:213], v[110:113]
	v_mfma_f32_16x16x32_bf16 v[106:109], v[234:237], v[210:213], v[106:109]
	v_mfma_f32_16x16x32_bf16 v[102:105], v[238:241], v[210:213], v[102:105]
	v_mfma_f32_16x16x32_bf16 v[98:101], v[242:245], v[210:213], v[98:101]
	v_mfma_f32_16x16x32_bf16 v[94:97], v[230:233], v[214:217], v[94:97]
	v_mfma_f32_16x16x32_bf16 v[90:93], v[234:237], v[214:217], v[90:93]
	v_mfma_f32_16x16x32_bf16 v[86:89], v[238:241], v[214:217], v[86:89]
	v_mfma_f32_16x16x32_bf16 v[82:85], v[242:245], v[214:217], v[82:85]
	v_mfma_f32_16x16x32_bf16 v[78:81], v[230:233], v[218:221], v[78:81]
	v_mfma_f32_16x16x32_bf16 v[74:77], v[234:237], v[218:221], v[74:77]
	v_mfma_f32_16x16x32_bf16 v[70:73], v[238:241], v[218:221], v[70:73]
	v_mfma_f32_16x16x32_bf16 v[66:69], v[242:245], v[218:221], v[66:69]
	v_mfma_f32_16x16x32_bf16 v[62:65], v[230:233], v[222:225], v[62:65]
	v_mfma_f32_16x16x32_bf16 v[58:61], v[234:237], v[222:225], v[58:61]
	v_mfma_f32_16x16x32_bf16 v[54:57], v[238:241], v[222:225], v[54:57]
	v_mfma_f32_16x16x32_bf16 v[50:53], v[242:245], v[222:225], v[50:53]
	v_mfma_f32_16x16x32_bf16 v[46:49], v[230:233], v[226:229], v[46:49]
	v_mfma_f32_16x16x32_bf16 v[42:45], v[234:237], v[226:229], v[42:45]
	v_mfma_f32_16x16x32_bf16 v[38:41], v[238:241], v[226:229], v[38:41]
	v_mfma_f32_16x16x32_bf16 v[34:37], v[242:245], v[226:229], v[34:37]

; #pragma unroll
;   for (int ks = KS0; ks < KS1; ++ks) {
;     bf16x8 af[8], bfr[4];
; #pragma unroll
;     for (int i = 0; i < 8; ++i) {
;       const int r = wm * 128 + i * 16 + (lane & 15);
;       af[i] = *(const bf16x8*)(S + r * 64 + (((ks * 4 + (lane >> 4)) ^ ((r >> 1) & 7)) << 3));
;     }
; #pragma unroll
;     for (int j = 0; j < 4; ++j) {
;       const int r = wn * 64 + j * 16 + (lane & 15);
;       bfr[j] = *(const bf16x8*)(S + 16384 + r * 64 + (((ks * 4 + (lane >> 4)) ^ ((r >> 1) & 7)) << 3));
;     }
;     __builtin_amdgcn_s_setprio(1);
; #pragma unroll
;     for (int i = 0; i < 8; ++i)
; #pragma unroll
;       for (int j = 0; j < 4; ++j) acc[i][j] = mfma16(bfr[j], af[i], acc[i][j]);
;     __builtin_amdgcn_s_setprio(0);
;   }
; }
; DI void g8_load1o(u32x4 (&r4)[4], const bf16_t* base, const unsigned (&off)[4]) {
; #pragma unroll
;   for (int i = 0; i < 4; ++i) r4[i] = *(const u32x4*)(base + off[i]);
; }
; DI void gemm8_accum(f32x4 (&acc)[8][4], const bf16_t* a, size_t lda, const bf16_t* b, size_t ldb, int nkb, bf16_t* L,
;                     const bool pre, const bf16_t* an, size_t ldan, const bf16_t* bn, size_t ldbn) {
;   const int tid = TID8(), lane = tid & 63, w = tid >> 6;
;   const int wm = w >> 2, wn = w & 3;
;   const int lrow = tid >> 3, lch = tid & 7;
;   u32x4 ra[4], rb[4];
;   unsigned offa[4], offb[4];
; #pragma unroll
;   for (int i = 0; i < 4; ++i) {
;     offa[i] = (unsigned)(lrow + 64 * i) * (unsigned)lda + (unsigned)(lch * 8);
;     offb[i] = (unsigned)(lrow + 64 * i) * (unsigned)ldb + (unsigned)(lch * 8);
;   }
;   if (!pre) {
;     g8_load1o(ra, a, offa);
;     g8_load1o(rb, b, offb);
;     __syncthreads();
;     g8_store(L, ra, rb, lrow, lch);
;   }
;   g8_load1o(ra, a + 64, offa);
;   g8_load1o(rb, b + 64, offb);
;   for (int kb = 0; kb + 2 < nkb; ++kb) {
;     __syncthreads();
;     g8_store1(L + ((kb + 1) & 1) * 32768, ra, lrow, lch);
;     g8_load1o(ra, a + (kb + 2) * 64, offa);
;     __builtin_amdgcn_sched_barrier(0);
;     g8_compute<0, 1>(acc, L + (kb & 1) * 32768, wm, wn, lane);
;     __builtin_amdgcn_sched_barrier(0);
;     g8_store1(L + ((kb + 1) & 1) * 32768 + 16384, rb, lrow, lch);
;     g8_load1o(rb, b + (kb + 2) * 64, offb);
;     __builtin_amdgcn_sched_barrier(0);
;     g8_compute<1, 2>(acc, L + (kb & 1) * 32768, wm, wn, lane);
;   }
.Lstg_780_a:
	s_waitcnt vmcnt(3)
	ds_write_b128 v193, v[146:149]
	ds_write_b128 v193, v[150:153] offset:8192
	ds_write_b128 v193, v[154:157] offset:16384
	ds_write_b128 v193, v[158:161] offset:24576
	s_add_u32 s54, s52, s0
	s_addc_u32 s55, s53, s1
	global_load_dwordx4 v[146:149], v187, s[54:55]
	global_load_dwordx4 v[150:153], v185, s[54:55]
	global_load_dwordx4 v[154:157], v183, s[54:55]
	global_load_dwordx4 v[158:161], v181, s[54:55]
	s_and_b32 s2, s2, 0x8000
	s_lshl_b32 s2, s2, 1
	v_lshl_add_u32 v194, v192, 1, s2
	v_add_u32_e32 v195, v194, v189
	ds_read_b128 v[198:201], v195
	ds_read_b128 v[206:209], v195 offset:2048
	ds_read_b128 v[210:213], v195 offset:4096
	ds_read_b128 v[214:217], v195 offset:6144
	ds_read_b128 v[218:221], v195 offset:8192
	ds_read_b128 v[222:225], v195 offset:10240
	ds_read_b128 v[226:229], v195 offset:12288
	ds_read_b128 v[230:233], v195 offset:14336
	v_add_u32_e32 v194, v194, v188
	ds_read_b128 v[234:237], v194 offset:32768
	ds_read_b128 v[238:241], v194 offset:34816
	ds_read_b128 v[242:245], v194 offset:36864
	ds_read_b128 v[246:249], v194 offset:38912
	s_waitcnt lgkmcnt(3)
	v_mfma_f32_16x16x32_bf16 v[2:5], v[234:237], v[198:201], v[2:5]
	s_waitcnt lgkmcnt(2)
	v_mfma_f32_16x16x32_bf16 v[6:9], v[238:241], v[198:201], v[6:9]
	s_waitcnt lgkmcnt(1)
	v_mfma_f32_16x16x32_bf16 v[10:13], v[242:245], v[198:201], v[10:13]
	s_waitcnt lgkmcnt(0)
	v_mfma_f32_16x16x32_bf16 v[14:17], v[246:249], v[198:201], v[14:17]
	v_mfma_f32_16x16x32_bf16 v[22:25], v[234:237], v[206:209], v[22:25]
	v_mfma_f32_16x16x32_bf16 v[30:33], v[238:241], v[206:209], v[30:33]
	v_mfma_f32_16x16x32_bf16 v[38:41], v[242:245], v[206:209], v[38:41]
	v_mfma_f32_16x16x32_bf16 v[46:49], v[246:249], v[206:209], v[46:49]
	v_mfma_f32_16x16x32_bf16 v[54:57], v[234:237], v[210:213], v[54:57]
	v_mfma_f32_16x16x32_bf16 v[62:65], v[238:241], v[210:213], v[62:65]
	v_mfma_f32_16x16x32_bf16 v[70:73], v[242:245], v[210:213], v[70:73]
	v_mfma_f32_16x16x32_bf16 v[78:81], v[246:249], v[210:213], v[78:81]
	v_mfma_f32_16x16x32_bf16 v[86:89], v[234:237], v[214:217], v[86:89]
	v_mfma_f32_16x16x32_bf16 v[94:97], v[238:241], v[214:217], v[94:97]
	v_mfma_f32_16x16x32_bf16 v[102:105], v[242:245], v[214:217], v[102:105]
	v_mfma_f32_16x16x32_bf16 v[110:113], v[246:249], v[214:217], v[110:113]
	v_mfma_f32_16x16x32_bf16 v[118:121], v[234:237], v[218:221], v[118:121]
	v_mfma_f32_16x16x32_bf16 v[126:129], v[238:241], v[218:221], v[126:129]
	v_mfma_f32_16x16x32_bf16 v[122:125], v[242:245], v[218:221], v[122:125]
	v_mfma_f32_16x16x32_bf16 v[114:117], v[246:249], v[218:221], v[114:117]
	v_mfma_f32_16x16x32_bf16 v[106:109], v[234:237], v[222:225], v[106:109]
	v_mfma_f32_16x16x32_bf16 v[98:101], v[238:241], v[222:225], v[98:101]
	v_mfma_f32_16x16x32_bf16 v[90:93], v[242:245], v[222:225], v[90:93]
	v_mfma_f32_16x16x32_bf16 v[82:85], v[246:249], v[222:225], v[82:85]
	v_mfma_f32_16x16x32_bf16 v[74:77], v[234:237], v[226:229], v[74:77]
	v_mfma_f32_16x16x32_bf16 v[66:69], v[238:241], v[226:229], v[66:69]
	v_mfma_f32_16x16x32_bf16 v[58:61], v[242:245], v[226:229], v[58:61]
	v_mfma_f32_16x16x32_bf16 v[50:53], v[246:249], v[226:229], v[50:53]
	v_mfma_f32_16x16x32_bf16 v[42:45], v[234:237], v[230:233], v[42:45]
	v_mfma_f32_16x16x32_bf16 v[34:37], v[238:241], v[230:233], v[34:37]
	v_mfma_f32_16x16x32_bf16 v[26:29], v[242:245], v[230:233], v[26:29]
	v_mfma_f32_16x16x32_bf16 v[18:21], v[246:249], v[230:233], v[18:21]
	s_waitcnt vmcnt(4)
	ds_write_b128 v193, v[130:133] offset:32768
	ds_write_b128 v193, v[138:141] offset:40960
	ds_write_b128 v193, v[134:137] offset:49152
	ds_write_b128 v193, v[142:145] offset:57344
	s_add_u32 s58, s56, s0
	s_addc_u32 s59, s57, s1
	global_load_dwordx4 v[130:133], v179, s[58:59]
	global_load_dwordx4 v[138:141], v177, s[58:59]
	global_load_dwordx4 v[134:137], v175, s[58:59]
	global_load_dwordx4 v[142:145], v173, s[58:59]
	v_lshl_add_u32 v193, v190, 1, s2
	v_add_u32_e32 v194, v193, v189
	ds_read_b128 v[198:201], v194
	ds_read_b128 v[206:209], v194 offset:2048
	ds_read_b128 v[210:213], v194 offset:4096
	ds_read_b128 v[214:217], v194 offset:6144
	ds_read_b128 v[218:221], v194 offset:8192
	ds_read_b128 v[222:225], v194 offset:10240
	ds_read_b128 v[226:229], v194 offset:12288
	ds_read_b128 v[230:233], v194 offset:14336
	v_add_u32_e32 v193, v193, v188
	ds_read_b128 v[234:237], v193 offset:32768
	ds_read_b128 v[238:241], v193 offset:34816
	ds_read_b128 v[242:245], v193 offset:36864
	ds_read_b128 v[246:249], v193 offset:38912
	s_cmp_lg_u32 s101, 0
	s_cbranch_scc1 .Lstg_780_b
	s_waitcnt lgkmcnt(3)
	v_mfma_f32_16x16x32_bf16 v[2:5], v[234:237], v[198:201], v[2:5]
	s_waitcnt lgkmcnt(2)
	v_mfma_f32_16x16x32_bf16 v[6:9], v[238:241], v[198:201], v[6:9]
	s_waitcnt lgkmcnt(1)
	v_mfma_f32_16x16x32_bf16 v[10:13], v[242:245], v[198:201], v[10:13]
	s_waitcnt lgkmcnt(0)
	v_mfma_f32_16x16x32_bf16 v[14:17], v[246:249], v[198:201], v[14:17]
	v_mfma_f32_16x16x32_bf16 v[22:25], v[234:237], v[206:209], v[22:25]
	v_mfma_f32_16x16x32_bf16 v[30:33], v[238:241], v[206:209], v[30:33]
	v_mfma_f32_16x16x32_bf16 v[38:41], v[242:245], v[206:209], v[38:41]
	v_mfma_f32_16x16x32_bf16 v[46:49], v[246:249], v[206:209], v[46:49]
	v_mfma_f32_16x16x32_bf16 v[54:57], v[234:237], v[210:213], v[54:57]
	v_mfma_f32_16x16x32_bf16 v[62:65], v[238:241], v[210:213], v[62:65]
	v_mfma_f32_16x16x32_bf16 v[70:73], v[242:245], v[210:213], v[70:73]
	v_mfma_f32_16x16x32_bf16 v[78:81], v[246:249], v[210:213], v[78:81]
	v_mfma_f32_16x16x32_bf16 v[86:89], v[234:237], v[214:217], v[86:89]
	v_mfma_f32_16x16x32_bf16 v[94:97], v[238:241], v[214:217], v[94:97]
	v_mfma_f32_16x16x32_bf16 v[102:105], v[242:245], v[214:217], v[102:105]
	v_mfma_f32_16x16x32_bf16 v[110:113], v[246:249], v[214:217], v[110:113]
	v_mfma_f32_16x16x32_bf16 v[118:121], v[234:237], v[218:221], v[118:121]
	v_mfma_f32_16x16x32_bf16 v[126:129], v[238:241], v[218:221], v[126:129]
	v_mfma_f32_16x16x32_bf16 v[122:125], v[242:245], v[218:221], v[122:125]
	v_mfma_f32_16x16x32_bf16 v[114:117], v[246:249], v[218:221], v[114:117]
	v_mfma_f32_16x16x32_bf16 v[106:109], v[234:237], v[222:225], v[106:109]
	v_mfma_f32_16x16x32_bf16 v[98:101], v[238:241], v[222:225], v[98:101]
	v_mfma_f32_16x16x32_bf16 v[90:93], v[242:245], v[222:225], v[90:93]
	v_mfma_f32_16x16x32_bf16 v[82:85], v[246:249], v[222:225], v[82:85]
	v_mfma_f32_16x16x32_bf16 v[74:77], v[234:237], v[226:229], v[74:77]
	v_mfma_f32_16x16x32_bf16 v[66:69], v[238:241], v[226:229], v[66:69]
	v_mfma_f32_16x16x32_bf16 v[58:61], v[242:245], v[226:229], v[58:61]
	v_mfma_f32_16x16x32_bf16 v[50:53], v[246:249], v[226:229], v[50:53]
	v_mfma_f32_16x16x32_bf16 v[42:45], v[234:237], v[230:233], v[42:45]
	v_mfma_f32_16x16x32_bf16 v[34:37], v[238:241], v[230:233], v[34:37]
	v_mfma_f32_16x16x32_bf16 v[26:29], v[242:245], v[230:233], v[26:29]
	v_mfma_f32_16x16x32_bf16 v[18:21], v[246:249], v[230:233], v[18:21]

; #pragma unroll
;   for (int ks = KS0; ks < KS1; ++ks) {
;     bf16x8 af[8], bfr[4];
; #pragma unroll
;     for (int i = 0; i < 8; ++i) {
;       const int r = wm * 128 + i * 16 + (lane & 15);
;       af[i] = *(const bf16x8*)(S + r * 64 + (((ks * 4 + (lane >> 4)) ^ ((r >> 1) & 7)) << 3));
;     }
; #pragma unroll
;     for (int j = 0; j < 4; ++j) {
;       const int r = wn * 64 + j * 16 + (lane & 15);
;       bfr[j] = *(const bf16x8*)(S + 16384 + r * 64 + (((ks * 4 + (lane >> 4)) ^ ((r >> 1) & 7)) << 3));
;     }
;     __builtin_amdgcn_s_setprio(1);
; #pragma unroll
;     for (int i = 0; i < 8; ++i)
; #pragma unroll
;       for (int j = 0; j < 4; ++j) acc[i][j] = mfma16(bfr[j], af[i], acc[i][j]);
;     __builtin_amdgcn_s_setprio(0);
;   }
; }
; DI void g8_load1o(u32x4 (&r4)[4], const bf16_t* base, const unsigned (&off)[4]) {
; #pragma unroll
;   for (int i = 0; i < 4; ++i) r4[i] = *(const u32x4*)(base + off[i]);
; }
; DI void gemm8_accum(f32x4 (&acc)[8][4], const bf16_t* a, size_t lda, const bf16_t* b, size_t ldb, int nkb, bf16_t* L,
;                     const bool pre, const bf16_t* an, size_t ldan, const bf16_t* bn, size_t ldbn) {
;   const int tid = TID8(), lane = tid & 63, w = tid >> 6;
;   const int wm = w >> 2, wn = w & 3;
;   const int lrow = tid >> 3, lch = tid & 7;
;   u32x4 ra[4], rb[4];
;   unsigned offa[4], offb[4];
; #pragma unroll
;   for (int i = 0; i < 4; ++i) {
;     offa[i] = (unsigned)(lrow + 64 * i) * (unsigned)lda + (unsigned)(lch * 8);
;     offb[i] = (unsigned)(lrow + 64 * i) * (unsigned)ldb + (unsigned)(lch * 8);
;   }
;   if (!pre) {
;     g8_load1o(ra, a, offa);
;     g8_load1o(rb, b, offb);
;     __syncthreads();
;     g8_store(L, ra, rb, lrow, lch);
;   }
;   g8_load1o(ra, a + 64, offa);
;   g8_load1o(rb, b + 64, offb);
;   for (int kb = 0; kb + 2 < nkb; ++kb) {
;     __syncthreads();
;     g8_store1(L + ((kb + 1) & 1) * 32768, ra, lrow, lch);
;     g8_load1o(ra, a + (kb + 2) * 64, offa);
;     __builtin_amdgcn_sched_barrier(0);
;     g8_compute<0, 1>(acc, L + (kb & 1) * 32768, wm, wn, lane);
;     __builtin_amdgcn_sched_barrier(0);
;     g8_store1(L + ((kb + 1) & 1) * 32768 + 16384, rb, lrow, lch);
;     g8_load1o(rb, b + (kb + 2) * 64, offb);
;     __builtin_amdgcn_sched_barrier(0);
;     g8_compute<1, 2>(acc, L + (kb & 1) * 32768, wm, wn, lane);
;   }
.Lstg_830_a:
	s_waitcnt vmcnt(4)
	ds_write_b128 v171, v[18:21]
	ds_write_b128 v171, v[22:25] offset:8192
	ds_write_b128 v171, v[26:29] offset:16384
	ds_write_b128 v171, v[30:33] offset:24576
	s_add_u32 s54, s52, s0
	s_addc_u32 s55, s53, s1
	global_load_dwordx4 v[18:21], v193, s[54:55]
	global_load_dwordx4 v[22:25], v191, s[54:55]
	global_load_dwordx4 v[26:29], v189, s[54:55]
	global_load_dwordx4 v[30:33], v187, s[54:55]
	s_and_b32 s2, s2, 0x8000
	s_lshl_b32 s2, s2, 1
	v_lshl_add_u32 v173, v169, 1, s2
	v_add_u32_e32 v175, v173, v195
	ds_read_b128 v[198:201], v175
	ds_read_b128 v[206:209], v175 offset:2048
	ds_read_b128 v[210:213], v175 offset:4096
	ds_read_b128 v[214:217], v175 offset:6144
	ds_read_b128 v[218:221], v175 offset:8192
	ds_read_b128 v[222:225], v175 offset:10240
	ds_read_b128 v[226:229], v175 offset:12288
	ds_read_b128 v[230:233], v175 offset:14336
	v_add_u32_e32 v173, v173, v194
	ds_read_b128 v[234:237], v173 offset:32768
	ds_read_b128 v[238:241], v173 offset:34816
	ds_read_b128 v[242:245], v173 offset:36864
	ds_read_b128 v[246:249], v173 offset:38912
	s_waitcnt lgkmcnt(3)
	v_mfma_f32_16x16x32_bf16 v[158:161], v[234:237], v[198:201], v[158:161]
	s_waitcnt lgkmcnt(2)
	v_mfma_f32_16x16x32_bf16 v[154:157], v[238:241], v[198:201], v[154:157]
	s_waitcnt lgkmcnt(1)
	v_mfma_f32_16x16x32_bf16 v[150:153], v[242:245], v[198:201], v[150:153]
	s_waitcnt lgkmcnt(0)
	v_mfma_f32_16x16x32_bf16 v[146:149], v[246:249], v[198:201], v[146:149]
	v_mfma_f32_16x16x32_bf16 v[142:145], v[234:237], v[206:209], v[142:145]
	v_mfma_f32_16x16x32_bf16 v[138:141], v[238:241], v[206:209], v[138:141]
	v_mfma_f32_16x16x32_bf16 v[134:137], v[242:245], v[206:209], v[134:137]
	v_mfma_f32_16x16x32_bf16 v[130:133], v[246:249], v[206:209], v[130:133]
	v_mfma_f32_16x16x32_bf16 v[126:129], v[234:237], v[210:213], v[126:129]
	v_mfma_f32_16x16x32_bf16 v[122:125], v[238:241], v[210:213], v[122:125]
	v_mfma_f32_16x16x32_bf16 v[118:121], v[242:245], v[210:213], v[118:121]
	v_mfma_f32_16x16x32_bf16 v[114:117], v[246:249], v[210:213], v[114:117]
	v_mfma_f32_16x16x32_bf16 v[110:113], v[234:237], v[214:217], v[110:113]
	v_mfma_f32_16x16x32_bf16 v[106:109], v[238:241], v[214:217], v[106:109]
	v_mfma_f32_16x16x32_bf16 v[102:105], v[242:245], v[214:217], v[102:105]
	v_mfma_f32_16x16x32_bf16 v[98:101], v[246:249], v[214:217], v[98:101]
	v_mfma_f32_16x16x32_bf16 v[94:97], v[234:237], v[218:221], v[94:97]
	v_mfma_f32_16x16x32_bf16 v[90:93], v[238:241], v[218:221], v[90:93]
	v_mfma_f32_16x16x32_bf16 v[86:89], v[242:245], v[218:221], v[86:89]
	v_mfma_f32_16x16x32_bf16 v[82:85], v[246:249], v[218:221], v[82:85]
	v_mfma_f32_16x16x32_bf16 v[78:81], v[234:237], v[222:225], v[78:81]
	v_mfma_f32_16x16x32_bf16 v[74:77], v[238:241], v[222:225], v[74:77]
	v_mfma_f32_16x16x32_bf16 v[70:73], v[242:245], v[222:225], v[70:73]
	v_mfma_f32_16x16x32_bf16 v[66:69], v[246:249], v[222:225], v[66:69]
	v_mfma_f32_16x16x32_bf16 v[62:65], v[234:237], v[226:229], v[62:65]
	v_mfma_f32_16x16x32_bf16 v[58:61], v[238:241], v[226:229], v[58:61]
	v_mfma_f32_16x16x32_bf16 v[54:57], v[242:245], v[226:229], v[54:57]
	v_mfma_f32_16x16x32_bf16 v[50:53], v[246:249], v[226:229], v[50:53]
	v_mfma_f32_16x16x32_bf16 v[46:49], v[234:237], v[230:233], v[46:49]
	v_mfma_f32_16x16x32_bf16 v[42:45], v[238:241], v[230:233], v[42:45]
	v_mfma_f32_16x16x32_bf16 v[38:41], v[242:245], v[230:233], v[38:41]
	v_mfma_f32_16x16x32_bf16 v[34:37], v[246:249], v[230:233], v[34:37]
	s_waitcnt vmcnt(4)
	ds_write_b128 v171, v[14:17] offset:32768
	ds_write_b128 v171, v[2:5] offset:40960
	ds_write_b128 v171, v[6:9] offset:49152
	ds_write_b128 v171, v[10:13] offset:57344
	s_add_u32 s58, s56, s0
	s_addc_u32 s59, s57, s1
	global_load_dwordx4 v[14:17], v185, s[58:59]
	global_load_dwordx4 v[2:5], v183, s[58:59]
	global_load_dwordx4 v[6:9], v181, s[58:59]
	global_load_dwordx4 v[10:13], v179, s[58:59]
	v_lshl_add_u32 v171, v205, 1, s2
	v_add_u32_e32 v173, v171, v195
	ds_read_b128 v[198:201], v173
	ds_read_b128 v[206:209], v173 offset:2048
	ds_read_b128 v[210:213], v173 offset:4096
	ds_read_b128 v[214:217], v173 offset:6144
	ds_read_b128 v[218:221], v173 offset:8192
	ds_read_b128 v[222:225], v173 offset:10240
	ds_read_b128 v[226:229], v173 offset:12288
	ds_read_b128 v[230:233], v173 offset:14336
	v_add_u32_e32 v171, v171, v194
	ds_read_b128 v[234:237], v171 offset:32768
	ds_read_b128 v[238:241], v171 offset:34816
	ds_read_b128 v[242:245], v171 offset:36864
	ds_read_b128 v[246:249], v171 offset:38912
	s_cmp_lg_u32 s101, 0
	s_cbranch_scc1 .Lstg_830_b
	s_waitcnt lgkmcnt(3)
	v_mfma_f32_16x16x32_bf16 v[158:161], v[234:237], v[198:201], v[158:161]
	s_waitcnt lgkmcnt(2)
	v_mfma_f32_16x16x32_bf16 v[154:157], v[238:241], v[198:201], v[154:157]
	s_waitcnt lgkmcnt(1)
	v_mfma_f32_16x16x32_bf16 v[150:153], v[242:245], v[198:201], v[150:153]
	s_waitcnt lgkmcnt(0)
	v_mfma_f32_16x16x32_bf16 v[146:149], v[246:249], v[198:201], v[146:149]
	v_mfma_f32_16x16x32_bf16 v[142:145], v[234:237], v[206:209], v[142:145]
	v_mfma_f32_16x16x32_bf16 v[138:141], v[238:241], v[206:209], v[138:141]
	v_mfma_f32_16x16x32_bf16 v[134:137], v[242:245], v[206:209], v[134:137]
	v_mfma_f32_16x16x32_bf16 v[130:133], v[246:249], v[206:209], v[130:133]
	v_mfma_f32_16x16x32_bf16 v[126:129], v[234:237], v[210:213], v[126:129]
	v_mfma_f32_16x16x32_bf16 v[122:125], v[238:241], v[210:213], v[122:125]
	v_mfma_f32_16x16x32_bf16 v[118:121], v[242:245], v[210:213], v[118:121]
	v_mfma_f32_16x16x32_bf16 v[114:117], v[246:249], v[210:213], v[114:117]
	v_mfma_f32_16x16x32_bf16 v[110:113], v[234:237], v[214:217], v[110:113]
	v_mfma_f32_16x16x32_bf16 v[106:109], v[238:241], v[214:217], v[106:109]
	v_mfma_f32_16x16x32_bf16 v[102:105], v[242:245], v[214:217], v[102:105]
	v_mfma_f32_16x16x32_bf16 v[98:101], v[246:249], v[214:217], v[98:101]
	v_mfma_f32_16x16x32_bf16 v[94:97], v[234:237], v[218:221], v[94:97]
	v_mfma_f32_16x16x32_bf16 v[90:93], v[238:241], v[218:221], v[90:93]
	v_mfma_f32_16x16x32_bf16 v[86:89], v[242:245], v[218:221], v[86:89]
	v_mfma_f32_16x16x32_bf16 v[82:85], v[246:249], v[218:221], v[82:85]
	v_mfma_f32_16x16x32_bf16 v[78:81], v[234:237], v[222:225], v[78:81]
	v_mfma_f32_16x16x32_bf16 v[74:77], v[238:241], v[222:225], v[74:77]
	v_mfma_f32_16x16x32_bf16 v[70:73], v[242:245], v[222:225], v[70:73]
	v_mfma_f32_16x16x32_bf16 v[66:69], v[246:249], v[222:225], v[66:69]
	v_mfma_f32_16x16x32_bf16 v[62:65], v[234:237], v[226:229], v[62:65]
	v_mfma_f32_16x16x32_bf16 v[58:61], v[238:241], v[226:229], v[58:61]
	v_mfma_f32_16x16x32_bf16 v[54:57], v[242:245], v[226:229], v[54:57]
	v_mfma_f32_16x16x32_bf16 v[50:53], v[246:249], v[226:229], v[50:53]
	v_mfma_f32_16x16x32_bf16 v[46:49], v[234:237], v[230:233], v[46:49]
	v_mfma_f32_16x16x32_bf16 v[42:45], v[238:241], v[230:233], v[42:45]
	v_mfma_f32_16x16x32_bf16 v[38:41], v[242:245], v[230:233], v[38:41]
	v_mfma_f32_16x16x32_bf16 v[34:37], v[246:249], v[230:233], v[34:37]

; #pragma unroll
;   for (int ks = KS0; ks < KS1; ++ks) {
;     bf16x8 af[8], bfr[4];
; #pragma unroll
;     for (int i = 0; i < 8; ++i) {
;       const int r = wm * 128 + i * 16 + (lane & 15);
;       af[i] = *(const bf16x8*)(S + r * 64 + (((ks * 4 + (lane >> 4)) ^ ((r >> 1) & 7)) << 3));
;     }
; #pragma unroll
;     for (int j = 0; j < 4; ++j) {
;       const int r = wn * 64 + j * 16 + (lane & 15);
;       bfr[j] = *(const bf16x8*)(S + 16384 + r * 64 + (((ks * 4 + (lane >> 4)) ^ ((r >> 1) & 7)) << 3));
;     }
;     __builtin_amdgcn_s_setprio(1);
; #pragma unroll
;     for (int i = 0; i < 8; ++i)
; #pragma unroll
;       for (int j = 0; j < 4; ++j) acc[i][j] = mfma16(bfr[j], af[i], acc[i][j]);
;     __builtin_amdgcn_s_setprio(0);
;   }
; }
; DI void g8_load1o(u32x4 (&r4)[4], const bf16_t* base, const unsigned (&off)[4]) {
; #pragma unroll
;   for (int i = 0; i < 4; ++i) r4[i] = *(const u32x4*)(base + off[i]);
; }
; DI void gemm8_accum(f32x4 (&acc)[8][4], const bf16_t* a, size_t lda, const bf16_t* b, size_t ldb, int nkb, bf16_t* L,
;                     const bool pre, const bf16_t* an, size_t ldan, const bf16_t* bn, size_t ldbn) {
;   const int tid = TID8(), lane = tid & 63, w = tid >> 6;
;   const int wm = w >> 2, wn = w & 3;
;   const int lrow = tid >> 3, lch = tid & 7;
;   u32x4 ra[4], rb[4];
;   unsigned offa[4], offb[4];
; #pragma unroll
;   for (int i = 0; i < 4; ++i) {
;     offa[i] = (unsigned)(lrow + 64 * i) * (unsigned)lda + (unsigned)(lch * 8);
;     offb[i] = (unsigned)(lrow + 64 * i) * (unsigned)ldb + (unsigned)(lch * 8);
;   }
;   if (!pre) {
;     g8_load1o(ra, a, offa);
;     g8_load1o(rb, b, offb);
;     __syncthreads();
;     g8_store(L, ra, rb, lrow, lch);
;   }
;   g8_load1o(ra, a + 64, offa);
;   g8_load1o(rb, b + 64, offb);
;   for (int kb = 0; kb + 2 < nkb; ++kb) {
;     __syncthreads();
;     g8_store1(L + ((kb + 1) & 1) * 32768, ra, lrow, lch);
;     g8_load1o(ra, a + (kb + 2) * 64, offa);
;     __builtin_amdgcn_sched_barrier(0);
;     g8_compute<0, 1>(acc, L + (kb & 1) * 32768, wm, wn, lane);
;     __builtin_amdgcn_sched_barrier(0);
;     g8_store1(L + ((kb + 1) & 1) * 32768 + 16384, rb, lrow, lch);
;     g8_load1o(rb, b + (kb + 2) * 64, offb);
;     __builtin_amdgcn_sched_barrier(0);
;     g8_compute<1, 2>(acc, L + (kb & 1) * 32768, wm, wn, lane);
;   }
.Lstg_892_a:
	s_waitcnt vmcnt(4)
	ds_write_b128 v167, v[22:25]
	ds_write_b128 v167, v[18:21] offset:8192
	ds_write_b128 v167, v[26:29] offset:16384
	ds_write_b128 v167, v[30:33] offset:24576
	s_add_u32 s54, s52, s0
	s_addc_u32 s55, s53, s1
	global_load_dwordx4 v[22:25], v185, s[54:55]
	global_load_dwordx4 v[26:29], v181, s[54:55]
	global_load_dwordx4 v[18:21], v183, s[54:55]
	global_load_dwordx4 v[30:33], v179, s[54:55]
	s_and_b32 s2, s2, 0x8000
	s_lshl_b32 s2, s2, 1
	v_lshl_add_u32 v169, v191, 1, s2
	v_add_u32_e32 v202, v169, v187
	ds_read_b128 v[192:195], v202
	ds_read_b128 v[198:201], v202 offset:2048
	ds_read_b128 v[206:209], v202 offset:4096
	ds_read_b128 v[210:213], v202 offset:6144
	ds_read_b128 v[214:217], v202 offset:8192
	ds_read_b128 v[218:221], v202 offset:10240
	ds_read_b128 v[222:225], v202 offset:12288
	ds_read_b128 v[226:229], v202 offset:14336
	v_add_u32_e32 v169, v169, v186
	ds_read_b128 v[230:233], v169 offset:32768
	ds_read_b128 v[234:237], v169 offset:34816
	ds_read_b128 v[238:241], v169 offset:36864
	ds_read_b128 v[242:245], v169 offset:38912
	s_waitcnt lgkmcnt(3)
	v_mfma_f32_16x16x32_bf16 v[158:161], v[230:233], v[192:195], v[158:161]
	s_waitcnt lgkmcnt(2)
	v_mfma_f32_16x16x32_bf16 v[154:157], v[234:237], v[192:195], v[154:157]
	s_waitcnt lgkmcnt(1)
	v_mfma_f32_16x16x32_bf16 v[150:153], v[238:241], v[192:195], v[150:153]
	s_waitcnt lgkmcnt(0)
	v_mfma_f32_16x16x32_bf16 v[146:149], v[242:245], v[192:195], v[146:149]
	v_mfma_f32_16x16x32_bf16 v[142:145], v[230:233], v[198:201], v[142:145]
	v_mfma_f32_16x16x32_bf16 v[138:141], v[234:237], v[198:201], v[138:141]
	v_mfma_f32_16x16x32_bf16 v[134:137], v[238:241], v[198:201], v[134:137]
	v_mfma_f32_16x16x32_bf16 v[130:133], v[242:245], v[198:201], v[130:133]
	v_mfma_f32_16x16x32_bf16 v[126:129], v[230:233], v[206:209], v[126:129]
	v_mfma_f32_16x16x32_bf16 v[122:125], v[234:237], v[206:209], v[122:125]
	v_mfma_f32_16x16x32_bf16 v[118:121], v[238:241], v[206:209], v[118:121]
	v_mfma_f32_16x16x32_bf16 v[114:117], v[242:245], v[206:209], v[114:117]
	v_mfma_f32_16x16x32_bf16 v[110:113], v[230:233], v[210:213], v[110:113]
	v_mfma_f32_16x16x32_bf16 v[106:109], v[234:237], v[210:213], v[106:109]
	v_mfma_f32_16x16x32_bf16 v[102:105], v[238:241], v[210:213], v[102:105]
	v_mfma_f32_16x16x32_bf16 v[98:101], v[242:245], v[210:213], v[98:101]
	v_mfma_f32_16x16x32_bf16 v[94:97], v[230:233], v[214:217], v[94:97]
	v_mfma_f32_16x16x32_bf16 v[90:93], v[234:237], v[214:217], v[90:93]
	v_mfma_f32_16x16x32_bf16 v[86:89], v[238:241], v[214:217], v[86:89]
	v_mfma_f32_16x16x32_bf16 v[82:85], v[242:245], v[214:217], v[82:85]
	v_mfma_f32_16x16x32_bf16 v[78:81], v[230:233], v[218:221], v[78:81]
	v_mfma_f32_16x16x32_bf16 v[74:77], v[234:237], v[218:221], v[74:77]
	v_mfma_f32_16x16x32_bf16 v[70:73], v[238:241], v[218:221], v[70:73]
	v_mfma_f32_16x16x32_bf16 v[66:69], v[242:245], v[218:221], v[66:69]
	v_mfma_f32_16x16x32_bf16 v[62:65], v[230:233], v[222:225], v[62:65]
	v_mfma_f32_16x16x32_bf16 v[58:61], v[234:237], v[222:225], v[58:61]
	v_mfma_f32_16x16x32_bf16 v[54:57], v[238:241], v[222:225], v[54:57]
	v_mfma_f32_16x16x32_bf16 v[50:53], v[242:245], v[222:225], v[50:53]
	v_mfma_f32_16x16x32_bf16 v[46:49], v[230:233], v[226:229], v[46:49]
	v_mfma_f32_16x16x32_bf16 v[42:45], v[234:237], v[226:229], v[42:45]
	v_mfma_f32_16x16x32_bf16 v[38:41], v[238:241], v[226:229], v[38:41]
	v_mfma_f32_16x16x32_bf16 v[34:37], v[242:245], v[226:229], v[34:37]
	s_waitcnt vmcnt(4)
	ds_write_b128 v167, v[14:17] offset:32768
	ds_write_b128 v167, v[2:5] offset:40960
	ds_write_b128 v167, v[6:9] offset:49152
	ds_write_b128 v167, v[10:13] offset:57344
	s_add_u32 s58, s56, s0
	s_addc_u32 s59, s57, s1
	global_load_dwordx4 v[14:17], v177, s[58:59]
	global_load_dwordx4 v[2:5], v175, s[58:59]
	global_load_dwordx4 v[6:9], v173, s[58:59]
	global_load_dwordx4 v[10:13], v171, s[58:59]
	v_lshl_add_u32 v167, v188, 1, s2
	v_add_u32_e32 v169, v167, v187
	ds_read_b128 v[192:195], v169
	ds_read_b128 v[198:201], v169 offset:2048
	ds_read_b128 v[206:209], v169 offset:4096
	ds_read_b128 v[210:213], v169 offset:6144
	ds_read_b128 v[214:217], v169 offset:8192
	ds_read_b128 v[218:221], v169 offset:10240
	ds_read_b128 v[222:225], v169 offset:12288
	ds_read_b128 v[226:229], v169 offset:14336
	v_add_u32_e32 v167, v167, v186
	ds_read_b128 v[230:233], v167 offset:32768
	ds_read_b128 v[234:237], v167 offset:34816
	ds_read_b128 v[238:241], v167 offset:36864
	ds_read_b128 v[242:245], v167 offset:38912
	s_cmp_lg_u32 s101, 0
	s_cbranch_scc1 .Lstg_892_b
	s_waitcnt lgkmcnt(3)
	v_mfma_f32_16x16x32_bf16 v[158:161], v[230:233], v[192:195], v[158:161]
	s_waitcnt lgkmcnt(2)
	v_mfma_f32_16x16x32_bf16 v[154:157], v[234:237], v[192:195], v[154:157]
	s_waitcnt lgkmcnt(1)
	v_mfma_f32_16x16x32_bf16 v[150:153], v[238:241], v[192:195], v[150:153]
	s_waitcnt lgkmcnt(0)
	v_mfma_f32_16x16x32_bf16 v[146:149], v[242:245], v[192:195], v[146:149]
	v_mfma_f32_16x16x32_bf16 v[142:145], v[230:233], v[198:201], v[142:145]
	v_mfma_f32_16x16x32_bf16 v[138:141], v[234:237], v[198:201], v[138:141]
	v_mfma_f32_16x16x32_bf16 v[134:137], v[238:241], v[198:201], v[134:137]
	v_mfma_f32_16x16x32_bf16 v[130:133], v[242:245], v[198:201], v[130:133]
	v_mfma_f32_16x16x32_bf16 v[126:129], v[230:233], v[206:209], v[126:129]
	v_mfma_f32_16x16x32_bf16 v[122:125], v[234:237], v[206:209], v[122:125]
	v_mfma_f32_16x16x32_bf16 v[118:121], v[238:241], v[206:209], v[118:121]
	v_mfma_f32_16x16x32_bf16 v[114:117], v[242:245], v[206:209], v[114:117]
	v_mfma_f32_16x16x32_bf16 v[110:113], v[230:233], v[210:213], v[110:113]
	v_mfma_f32_16x16x32_bf16 v[106:109], v[234:237], v[210:213], v[106:109]
	v_mfma_f32_16x16x32_bf16 v[102:105], v[238:241], v[210:213], v[102:105]
	v_mfma_f32_16x16x32_bf16 v[98:101], v[242:245], v[210:213], v[98:101]
	v_mfma_f32_16x16x32_bf16 v[94:97], v[230:233], v[214:217], v[94:97]
	v_mfma_f32_16x16x32_bf16 v[90:93], v[234:237], v[214:217], v[90:93]
	v_mfma_f32_16x16x32_bf16 v[86:89], v[238:241], v[214:217], v[86:89]
	v_mfma_f32_16x16x32_bf16 v[82:85], v[242:245], v[214:217], v[82:85]
	v_mfma_f32_16x16x32_bf16 v[78:81], v[230:233], v[218:221], v[78:81]
	v_mfma_f32_16x16x32_bf16 v[74:77], v[234:237], v[218:221], v[74:77]
	v_mfma_f32_16x16x32_bf16 v[70:73], v[238:241], v[218:221], v[70:73]
	v_mfma_f32_16x16x32_bf16 v[66:69], v[242:245], v[218:221], v[66:69]
	v_mfma_f32_16x16x32_bf16 v[62:65], v[230:233], v[222:225], v[62:65]
	v_mfma_f32_16x16x32_bf16 v[58:61], v[234:237], v[222:225], v[58:61]
	v_mfma_f32_16x16x32_bf16 v[54:57], v[238:241], v[222:225], v[54:57]
	v_mfma_f32_16x16x32_bf16 v[50:53], v[242:245], v[222:225], v[50:53]
	v_mfma_f32_16x16x32_bf16 v[46:49], v[230:233], v[226:229], v[46:49]
	v_mfma_f32_16x16x32_bf16 v[42:45], v[234:237], v[226:229], v[42:45]
	v_mfma_f32_16x16x32_bf16 v[38:41], v[238:241], v[226:229], v[38:41]
	v_mfma_f32_16x16x32_bf16 v[34:37], v[242:245], v[226:229], v[34:37]

; DI f32x4 mfma16(bf16x8 a, bf16x8 b, f32x4 c) { return __builtin_amdgcn_mfma_f32_16x16x32_bf16(a, b, c, 0, 0, 0); }
; #pragma unroll
;   for (int ks = KS0; ks < KS1; ++ks) {
;     bf16x8 af[8], bfr[4];
; #pragma unroll
;     for (int i = 0; i < 8; ++i) {
;       const int r = wm * 128 + i * 16 + (lane & 15);
;       af[i] = *(const bf16x8*)(S + r * 64 + (((ks * 4 + (lane >> 4)) ^ ((r >> 1) & 7)) << 3));
;     }
; #pragma unroll
;     for (int j = 0; j < 4; ++j) {
;       const int r = wn * 64 + j * 16 + (lane & 15);
;       bfr[j] = *(const bf16x8*)(S + 16384 + r * 64 + (((ks * 4 + (lane >> 4)) ^ ((r >> 1) & 7)) << 3));
;     }
;     __builtin_amdgcn_s_setprio(1);
; #pragma unroll
;     for (int i = 0; i < 8; ++i)
; #pragma unroll
;       for (int j = 0; j < 4; ++j) acc[i][j] = mfma16(bfr[j], af[i], acc[i][j]);
;     __builtin_amdgcn_s_setprio(0);
;   }
; }
; DI void gemm8_accum(f32x4 (&acc)[8][4], const bf16_t* a, size_t lda, const bf16_t* b, size_t ldb, int nkb, bf16_t* L,
;                     const bool pre, const bf16_t* an, size_t ldan, const bf16_t* bn, size_t ldbn) {
;     ...
;   for (int kb = 0; kb + 2 < nkb; ++kb) {
;     __syncthreads();
;     g8_store1(L + ((kb + 1) & 1) * 32768, ra, lrow, lch);
;     g8_load1o(ra, a + (kb + 2) * 64, offa);
;     __builtin_amdgcn_sched_barrier(0);
;     g8_compute<0, 1>(acc, L + (kb & 1) * 32768, wm, wn, lane);
;     __builtin_amdgcn_sched_barrier(0);
;     g8_store1(L + ((kb + 1) & 1) * 32768 + 16384, rb, lrow, lch);
;     g8_load1o(rb, b + (kb + 2) * 64, offb);
;     __builtin_amdgcn_sched_barrier(0);
;     g8_compute<1, 2>(acc, L + (kb & 1) * 32768, wm, wn, lane);
;   }
.Lstg_942_a:
	s_waitcnt vmcnt(4)
	ds_write_b128 v167, v[22:25]
	ds_write_b128 v167, v[18:21] offset:8192
	ds_write_b128 v167, v[26:29] offset:16384
	ds_write_b128 v167, v[30:33] offset:24576
	s_add_u32 s54, s52, s0
	s_addc_u32 s55, s53, s1
	global_load_dwordx4 v[22:25], v185, s[54:55]
	global_load_dwordx4 v[26:29], v181, s[54:55]
	global_load_dwordx4 v[18:21], v183, s[54:55]
	global_load_dwordx4 v[30:33], v179, s[54:55]
	s_and_b32 s2, s2, 0x8000
	s_lshl_b32 s2, s2, 1
	v_lshl_add_u32 v169, v191, 1, s2
	v_add_u32_e32 v222, v169, v187
	ds_read_b128 v[192:195], v222
	ds_read_b128 v[198:201], v222 offset:2048
	ds_read_b128 v[202:205], v222 offset:4096
	ds_read_b128 v[206:209], v222 offset:6144
	ds_read_b128 v[210:213], v222 offset:8192
	ds_read_b128 v[214:217], v222 offset:10240
	ds_read_b128 v[218:221], v222 offset:12288
	ds_read_b128 v[222:225], v222 offset:14336
	v_add_u32_e32 v169, v169, v186
	ds_read_b128 v[226:229], v169 offset:32768
	ds_read_b128 v[230:233], v169 offset:34816
	ds_read_b128 v[234:237], v169 offset:36864
	ds_read_b128 v[238:241], v169 offset:38912
	s_waitcnt lgkmcnt(3)
	v_mfma_f32_16x16x32_bf16 v[158:161], v[226:229], v[192:195], v[158:161]
	s_waitcnt lgkmcnt(2)
	v_mfma_f32_16x16x32_bf16 v[154:157], v[230:233], v[192:195], v[154:157]
	s_waitcnt lgkmcnt(1)
	v_mfma_f32_16x16x32_bf16 v[150:153], v[234:237], v[192:195], v[150:153]
	s_waitcnt lgkmcnt(0)
	v_mfma_f32_16x16x32_bf16 v[146:149], v[238:241], v[192:195], v[146:149]
	v_mfma_f32_16x16x32_bf16 v[142:145], v[226:229], v[198:201], v[142:145]
	v_mfma_f32_16x16x32_bf16 v[138:141], v[230:233], v[198:201], v[138:141]
	v_mfma_f32_16x16x32_bf16 v[134:137], v[234:237], v[198:201], v[134:137]
	v_mfma_f32_16x16x32_bf16 v[130:133], v[238:241], v[198:201], v[130:133]
	v_mfma_f32_16x16x32_bf16 v[126:129], v[226:229], v[202:205], v[126:129]
	v_mfma_f32_16x16x32_bf16 v[122:125], v[230:233], v[202:205], v[122:125]
	v_mfma_f32_16x16x32_bf16 v[118:121], v[234:237], v[202:205], v[118:121]
	v_mfma_f32_16x16x32_bf16 v[114:117], v[238:241], v[202:205], v[114:117]
	v_mfma_f32_16x16x32_bf16 v[110:113], v[226:229], v[206:209], v[110:113]
	v_mfma_f32_16x16x32_bf16 v[106:109], v[230:233], v[206:209], v[106:109]
	v_mfma_f32_16x16x32_bf16 v[102:105], v[234:237], v[206:209], v[102:105]
	v_mfma_f32_16x16x32_bf16 v[98:101], v[238:241], v[206:209], v[98:101]
	v_mfma_f32_16x16x32_bf16 v[94:97], v[226:229], v[210:213], v[94:97]
	v_mfma_f32_16x16x32_bf16 v[90:93], v[230:233], v[210:213], v[90:93]
	v_mfma_f32_16x16x32_bf16 v[86:89], v[234:237], v[210:213], v[86:89]
	v_mfma_f32_16x16x32_bf16 v[82:85], v[238:241], v[210:213], v[82:85]
	v_mfma_f32_16x16x32_bf16 v[78:81], v[226:229], v[214:217], v[78:81]
	v_mfma_f32_16x16x32_bf16 v[74:77], v[230:233], v[214:217], v[74:77]
	v_mfma_f32_16x16x32_bf16 v[70:73], v[234:237], v[214:217], v[70:73]
	v_mfma_f32_16x16x32_bf16 v[66:69], v[238:241], v[214:217], v[66:69]
	v_mfma_f32_16x16x32_bf16 v[62:65], v[226:229], v[218:221], v[62:65]
	v_mfma_f32_16x16x32_bf16 v[58:61], v[230:233], v[218:221], v[58:61]
	v_mfma_f32_16x16x32_bf16 v[54:57], v[234:237], v[218:221], v[54:57]
	v_mfma_f32_16x16x32_bf16 v[50:53], v[238:241], v[218:221], v[50:53]
	v_mfma_f32_16x16x32_bf16 v[46:49], v[226:229], v[222:225], v[46:49]
	v_mfma_f32_16x16x32_bf16 v[42:45], v[230:233], v[222:225], v[42:45]
	v_mfma_f32_16x16x32_bf16 v[38:41], v[234:237], v[222:225], v[38:41]
	v_mfma_f32_16x16x32_bf16 v[34:37], v[238:241], v[222:225], v[34:37]
	s_waitcnt vmcnt(4)
	ds_write_b128 v167, v[14:17] offset:32768
	ds_write_b128 v167, v[2:5] offset:40960
	ds_write_b128 v167, v[6:9] offset:49152
	ds_write_b128 v167, v[10:13] offset:57344
	s_add_u32 s58, s56, s0
	s_addc_u32 s59, s57, s1
	global_load_dwordx4 v[14:17], v177, s[58:59]
	global_load_dwordx4 v[2:5], v175, s[58:59]
	global_load_dwordx4 v[6:9], v173, s[58:59]
	global_load_dwordx4 v[10:13], v171, s[58:59]
	v_lshl_add_u32 v167, v188, 1, s2
	v_add_u32_e32 v169, v167, v187
	ds_read_b128 v[192:195], v169
	ds_read_b128 v[198:201], v169 offset:2048
	ds_read_b128 v[202:205], v169 offset:4096
	ds_read_b128 v[206:209], v169 offset:6144
	ds_read_b128 v[210:213], v169 offset:8192
	ds_read_b128 v[214:217], v169 offset:10240
	ds_read_b128 v[218:221], v169 offset:12288
	ds_read_b128 v[222:225], v169 offset:14336
	v_add_u32_e32 v167, v167, v186
	ds_read_b128 v[226:229], v167 offset:32768
	ds_read_b128 v[230:233], v167 offset:34816
	ds_read_b128 v[234:237], v167 offset:36864
	ds_read_b128 v[238:241], v167 offset:38912
	s_cmp_lg_u32 s101, 0
	s_cbranch_scc1 .Lstg_942_b
	s_waitcnt lgkmcnt(3)
	v_mfma_f32_16x16x32_bf16 v[158:161], v[226:229], v[192:195], v[158:161]
	s_waitcnt lgkmcnt(2)
	v_mfma_f32_16x16x32_bf16 v[154:157], v[230:233], v[192:195], v[154:157]
	s_waitcnt lgkmcnt(1)
	v_mfma_f32_16x16x32_bf16 v[150:153], v[234:237], v[192:195], v[150:153]
	s_waitcnt lgkmcnt(0)
	v_mfma_f32_16x16x32_bf16 v[146:149], v[238:241], v[192:195], v[146:149]
	v_mfma_f32_16x16x32_bf16 v[142:145], v[226:229], v[198:201], v[142:145]
	v_mfma_f32_16x16x32_bf16 v[138:141], v[230:233], v[198:201], v[138:141]
	v_mfma_f32_16x16x32_bf16 v[134:137], v[234:237], v[198:201], v[134:137]
	v_mfma_f32_16x16x32_bf16 v[130:133], v[238:241], v[198:201], v[130:133]
	v_mfma_f32_16x16x32_bf16 v[126:129], v[226:229], v[202:205], v[126:129]
	v_mfma_f32_16x16x32_bf16 v[122:125], v[230:233], v[202:205], v[122:125]
	v_mfma_f32_16x16x32_bf16 v[118:121], v[234:237], v[202:205], v[118:121]
	v_mfma_f32_16x16x32_bf16 v[114:117], v[238:241], v[202:205], v[114:117]
	v_mfma_f32_16x16x32_bf16 v[110:113], v[226:229], v[206:209], v[110:113]
	v_mfma_f32_16x16x32_bf16 v[106:109], v[230:233], v[206:209], v[106:109]
	v_mfma_f32_16x16x32_bf16 v[102:105], v[234:237], v[206:209], v[102:105]
	v_mfma_f32_16x16x32_bf16 v[98:101], v[238:241], v[206:209], v[98:101]
	v_mfma_f32_16x16x32_bf16 v[94:97], v[226:229], v[210:213], v[94:97]
	v_mfma_f32_16x16x32_bf16 v[90:93], v[230:233], v[210:213], v[90:93]
	v_mfma_f32_16x16x32_bf16 v[86:89], v[234:237], v[210:213], v[86:89]
	v_mfma_f32_16x16x32_bf16 v[82:85], v[238:241], v[210:213], v[82:85]
	v_mfma_f32_16x16x32_bf16 v[78:81], v[226:229], v[214:217], v[78:81]
	v_mfma_f32_16x16x32_bf16 v[74:77], v[230:233], v[214:217], v[74:77]
	v_mfma_f32_16x16x32_bf16 v[70:73], v[234:237], v[214:217], v[70:73]
	v_mfma_f32_16x16x32_bf16 v[66:69], v[238:241], v[214:217], v[66:69]
	v_mfma_f32_16x16x32_bf16 v[62:65], v[226:229], v[218:221], v[62:65]
	v_mfma_f32_16x16x32_bf16 v[58:61], v[230:233], v[218:221], v[58:61]
	v_mfma_f32_16x16x32_bf16 v[54:57], v[234:237], v[218:221], v[54:57]
	v_mfma_f32_16x16x32_bf16 v[50:53], v[238:241], v[218:221], v[50:53]
	v_mfma_f32_16x16x32_bf16 v[46:49], v[226:229], v[222:225], v[46:49]
	v_mfma_f32_16x16x32_bf16 v[42:45], v[230:233], v[222:225], v[42:45]
	v_mfma_f32_16x16x32_bf16 v[38:41], v[234:237], v[222:225], v[38:41]
	v_mfma_f32_16x16x32_bf16 v[34:37], v[238:241], v[222:225], v[34:37]

; DI f32x4 mfma16(bf16x8 a, bf16x8 b, f32x4 c) { return __builtin_amdgcn_mfma_f32_16x16x32_bf16(a, b, c, 0, 0, 0); }
; #pragma unroll
;   for (int ks = KS0; ks < KS1; ++ks) {
;     bf16x8 af[8], bfr[4];
; #pragma unroll
;     for (int i = 0; i < 8; ++i) {
;       const int r = wm * 128 + i * 16 + (lane & 15);
;       af[i] = *(const bf16x8*)(S + r * 64 + (((ks * 4 + (lane >> 4)) ^ ((r >> 1) & 7)) << 3));
;     }
; #pragma unroll
;     for (int j = 0; j < 4; ++j) {
;       const int r = wn * 64 + j * 16 + (lane & 15);
;       bfr[j] = *(const bf16x8*)(S + 16384 + r * 64 + (((ks * 4 + (lane >> 4)) ^ ((r >> 1) & 7)) << 3));
;     }
;     __builtin_amdgcn_s_setprio(1);
; #pragma unroll
;     for (int i = 0; i < 8; ++i)
; #pragma unroll
;       for (int j = 0; j < 4; ++j) acc[i][j] = mfma16(bfr[j], af[i], acc[i][j]);
;     __builtin_amdgcn_s_setprio(0);
;   }
; }
; DI void gemm8_accum(f32x4 (&acc)[8][4], const bf16_t* a, size_t lda, const bf16_t* b, size_t ldb, int nkb, bf16_t* L,
;                     const bool pre, const bf16_t* an, size_t ldan, const bf16_t* bn, size_t ldbn) {
;     ...
;   for (int kb = 0; kb + 2 < nkb; ++kb) {
;     __syncthreads();
;     g8_store1(L + ((kb + 1) & 1) * 32768, ra, lrow, lch);
;     g8_load1o(ra, a + (kb + 2) * 64, offa);
;     __builtin_amdgcn_sched_barrier(0);
;     g8_compute<0, 1>(acc, L + (kb & 1) * 32768, wm, wn, lane);
;     __builtin_amdgcn_sched_barrier(0);
;     g8_store1(L + ((kb + 1) & 1) * 32768 + 16384, rb, lrow, lch);
;     g8_load1o(rb, b + (kb + 2) * 64, offb);
;     __builtin_amdgcn_sched_barrier(0);
;     g8_compute<1, 2>(acc, L + (kb & 1) * 32768, wm, wn, lane);
;   }
.Lstg_1007_a:
	s_waitcnt vmcnt(4)
	ds_write_b128 v0, v[34:37]
	ds_write_b128 v0, v[42:45] offset:8192
	ds_write_b128 v0, v[54:57] offset:16384
	ds_write_b128 v0, v[94:97] offset:24576
	s_add_u32 s54, s52, s0
	s_addc_u32 s55, s53, s1
	global_load_dwordx4 v[34:37], v179, s[54:55]
	global_load_dwordx4 v[42:45], v177, s[54:55]
	global_load_dwordx4 v[54:57], v175, s[54:55]
	global_load_dwordx4 v[94:97], v173, s[54:55]
	s_and_b32 s2, s2, 0x8000
	s_lshl_b32 s2, s2, 1
	v_lshl_add_u32 v191, v186, 1, s2
	v_add_u32_e32 v222, v191, v181
	ds_read_b128 v[192:195], v222
	ds_read_b128 v[198:201], v222 offset:2048
	ds_read_b128 v[202:205], v222 offset:4096
	ds_read_b128 v[206:209], v222 offset:6144
	ds_read_b128 v[210:213], v222 offset:8192
	ds_read_b128 v[214:217], v222 offset:10240
	ds_read_b128 v[218:221], v222 offset:12288
	ds_read_b128 v[222:225], v222 offset:14336
	v_add_u32_e32 v191, v191, v180
	ds_read_b128 v[226:229], v191 offset:32768
	ds_read_b128 v[230:233], v191 offset:34816
	ds_read_b128 v[234:237], v191 offset:36864
	ds_read_b128 v[238:241], v191 offset:38912
	s_waitcnt lgkmcnt(3)
	v_mfma_f32_16x16x32_bf16 v[158:161], v[226:229], v[192:195], v[158:161]
	s_waitcnt lgkmcnt(2)
	v_mfma_f32_16x16x32_bf16 v[154:157], v[230:233], v[192:195], v[154:157]
	s_waitcnt lgkmcnt(1)
	v_mfma_f32_16x16x32_bf16 v[150:153], v[234:237], v[192:195], v[150:153]
	s_waitcnt lgkmcnt(0)
	v_mfma_f32_16x16x32_bf16 v[146:149], v[238:241], v[192:195], v[146:149]
	v_mfma_f32_16x16x32_bf16 v[142:145], v[226:229], v[198:201], v[142:145]
	v_mfma_f32_16x16x32_bf16 v[138:141], v[230:233], v[198:201], v[138:141]
	v_mfma_f32_16x16x32_bf16 v[134:137], v[234:237], v[198:201], v[134:137]
	v_mfma_f32_16x16x32_bf16 v[130:133], v[238:241], v[198:201], v[130:133]
	v_mfma_f32_16x16x32_bf16 v[126:129], v[226:229], v[202:205], v[126:129]
	v_mfma_f32_16x16x32_bf16 v[122:125], v[230:233], v[202:205], v[122:125]
	v_mfma_f32_16x16x32_bf16 v[118:121], v[234:237], v[202:205], v[118:121]
	v_mfma_f32_16x16x32_bf16 v[114:117], v[238:241], v[202:205], v[114:117]
	v_mfma_f32_16x16x32_bf16 v[110:113], v[226:229], v[206:209], v[110:113]
	v_mfma_f32_16x16x32_bf16 v[106:109], v[230:233], v[206:209], v[106:109]
	v_mfma_f32_16x16x32_bf16 v[102:105], v[234:237], v[206:209], v[102:105]
	v_mfma_f32_16x16x32_bf16 v[98:101], v[238:241], v[206:209], v[98:101]
	v_mfma_f32_16x16x32_bf16 v[90:93], v[226:229], v[210:213], v[90:93]
	v_mfma_f32_16x16x32_bf16 v[86:89], v[230:233], v[210:213], v[86:89]
	v_mfma_f32_16x16x32_bf16 v[82:85], v[234:237], v[210:213], v[82:85]
	v_mfma_f32_16x16x32_bf16 v[78:81], v[238:241], v[210:213], v[78:81]
	v_mfma_f32_16x16x32_bf16 v[74:77], v[226:229], v[214:217], v[74:77]
	v_mfma_f32_16x16x32_bf16 v[70:73], v[230:233], v[214:217], v[70:73]
	v_mfma_f32_16x16x32_bf16 v[66:69], v[234:237], v[214:217], v[66:69]
	v_mfma_f32_16x16x32_bf16 v[62:65], v[238:241], v[214:217], v[62:65]
	v_mfma_f32_16x16x32_bf16 v[58:61], v[226:229], v[218:221], v[58:61]
	v_mfma_f32_16x16x32_bf16 v[50:53], v[230:233], v[218:221], v[50:53]
	v_mfma_f32_16x16x32_bf16 v[46:49], v[234:237], v[218:221], v[46:49]
	v_mfma_f32_16x16x32_bf16 v[38:41], v[238:241], v[218:221], v[38:41]
	v_mfma_f32_16x16x32_bf16 v[30:33], v[226:229], v[222:225], v[30:33]
	v_mfma_f32_16x16x32_bf16 v[26:29], v[230:233], v[222:225], v[26:29]
	v_mfma_f32_16x16x32_bf16 v[22:25], v[234:237], v[222:225], v[22:25]
	v_mfma_f32_16x16x32_bf16 v[18:21], v[238:241], v[222:225], v[18:21]
	s_waitcnt vmcnt(4)
	ds_write_b128 v0, v[14:17] offset:32768
	ds_write_b128 v0, v[2:5] offset:40960
	ds_write_b128 v0, v[6:9] offset:49152
	ds_write_b128 v0, v[10:13] offset:57344
	s_add_u32 s58, s56, s0
	s_addc_u32 s59, s57, s1
	global_load_dwordx4 v[14:17], v171, s[58:59]
	global_load_dwordx4 v[2:5], v169, s[58:59]
	global_load_dwordx4 v[6:9], v167, s[58:59]
	global_load_dwordx4 v[10:13], v165, s[58:59]
	v_lshl_add_u32 v0, v182, 1, s2
	v_add_u32_e32 v191, v0, v181
	ds_read_b128 v[192:195], v191
	ds_read_b128 v[198:201], v191 offset:2048
	ds_read_b128 v[202:205], v191 offset:4096
	ds_read_b128 v[206:209], v191 offset:6144
	ds_read_b128 v[210:213], v191 offset:8192
	ds_read_b128 v[214:217], v191 offset:10240
	ds_read_b128 v[218:221], v191 offset:12288
	ds_read_b128 v[222:225], v191 offset:14336
	v_add_u32_e32 v0, v0, v180
	ds_read_b128 v[226:229], v0 offset:32768
	ds_read_b128 v[230:233], v0 offset:34816
	ds_read_b128 v[234:237], v0 offset:36864
	ds_read_b128 v[238:241], v0 offset:38912
	s_cmp_lg_u32 s101, 0
	s_cbranch_scc1 .Lstg_1007_b
	s_waitcnt lgkmcnt(3)
	v_mfma_f32_16x16x32_bf16 v[158:161], v[226:229], v[192:195], v[158:161]
	s_waitcnt lgkmcnt(2)
	v_mfma_f32_16x16x32_bf16 v[154:157], v[230:233], v[192:195], v[154:157]
	s_waitcnt lgkmcnt(1)
	v_mfma_f32_16x16x32_bf16 v[150:153], v[234:237], v[192:195], v[150:153]
	s_waitcnt lgkmcnt(0)
	v_mfma_f32_16x16x32_bf16 v[146:149], v[238:241], v[192:195], v[146:149]
	v_mfma_f32_16x16x32_bf16 v[142:145], v[226:229], v[198:201], v[142:145]
	v_mfma_f32_16x16x32_bf16 v[138:141], v[230:233], v[198:201], v[138:141]
	v_mfma_f32_16x16x32_bf16 v[134:137], v[234:237], v[198:201], v[134:137]
	v_mfma_f32_16x16x32_bf16 v[130:133], v[238:241], v[198:201], v[130:133]
	v_mfma_f32_16x16x32_bf16 v[126:129], v[226:229], v[202:205], v[126:129]
	v_mfma_f32_16x16x32_bf16 v[122:125], v[230:233], v[202:205], v[122:125]
	v_mfma_f32_16x16x32_bf16 v[118:121], v[234:237], v[202:205], v[118:121]
	v_mfma_f32_16x16x32_bf16 v[114:117], v[238:241], v[202:205], v[114:117]
	v_mfma_f32_16x16x32_bf16 v[110:113], v[226:229], v[206:209], v[110:113]
	v_mfma_f32_16x16x32_bf16 v[106:109], v[230:233], v[206:209], v[106:109]
	v_mfma_f32_16x16x32_bf16 v[102:105], v[234:237], v[206:209], v[102:105]
	v_mfma_f32_16x16x32_bf16 v[98:101], v[238:241], v[206:209], v[98:101]
	v_mfma_f32_16x16x32_bf16 v[90:93], v[226:229], v[210:213], v[90:93]
	v_mfma_f32_16x16x32_bf16 v[86:89], v[230:233], v[210:213], v[86:89]
	v_mfma_f32_16x16x32_bf16 v[82:85], v[234:237], v[210:213], v[82:85]
	v_mfma_f32_16x16x32_bf16 v[78:81], v[238:241], v[210:213], v[78:81]
	v_mfma_f32_16x16x32_bf16 v[74:77], v[226:229], v[214:217], v[74:77]
	v_mfma_f32_16x16x32_bf16 v[70:73], v[230:233], v[214:217], v[70:73]
	v_mfma_f32_16x16x32_bf16 v[66:69], v[234:237], v[214:217], v[66:69]
	v_mfma_f32_16x16x32_bf16 v[62:65], v[238:241], v[214:217], v[62:65]
	v_mfma_f32_16x16x32_bf16 v[58:61], v[226:229], v[218:221], v[58:61]
	v_mfma_f32_16x16x32_bf16 v[50:53], v[230:233], v[218:221], v[50:53]
	v_mfma_f32_16x16x32_bf16 v[46:49], v[234:237], v[218:221], v[46:49]
	v_mfma_f32_16x16x32_bf16 v[38:41], v[238:241], v[218:221], v[38:41]
	v_mfma_f32_16x16x32_bf16 v[30:33], v[226:229], v[222:225], v[30:33]
	v_mfma_f32_16x16x32_bf16 v[26:29], v[230:233], v[222:225], v[26:29]
	v_mfma_f32_16x16x32_bf16 v[22:25], v[234:237], v[222:225], v[22:25]
	v_mfma_f32_16x16x32_bf16 v[18:21], v[238:241], v[222:225], v[18:21]
